# v104 + conv item row loop: ring of four register sets (loads three rows ahead), wait counts leave younger loads and row stores in flight
# baseline (speedup 1.0000x reference)
; __device__ __forceinline__ float bflo(unsigned w) { return __uint_as_float(w << 16); }
; __device__ __forceinline__ float bfhi(unsigned w) { return __uint_as_float(w & 0xffff0000u); }
; __device__ __forceinline__ int opq(int x) { asm volatile("" : "+v"(x)); return x; }
; __device__ __forceinline__ void item_conv(const Params& p, int l, int it) {
;     const int tid = opq(threadIdx.x), cc = tid & 63, tb = tid >> 6; const int r0 = it * 128 + tb * 16, s0 = r0 & 4095;
;     float w0[8], w1[8], w2[8];
; #pragma unroll
;     for (int e = 0; e < 8; ++e) { w0[e] = p.conv_w[(l * 3 + 0) * 512 + cc * 8 + e]; w1[e] = p.conv_w[(l * 3 + 1) * 512 + cc * 8 + e]; w2[e] = p.conv_w[(l * 3 + 2) * 512 + cc * 8 + e]; }
;     float y2[8], y1[8];
;     auto ld8 = [&](int r, int col, float* o) { const u32x4 w = *(const u32x4*)(p.proj + (size_t)r * NP + col + cc * 8);
; #pragma unroll
;         for (int e = 0; e < 4; ++e) { o[2 * e] = bflo(w[e]); o[2 * e + 1] = bfhi(w[e]); } };
;     auto ycx = [&](int r, float* o) { float a[8], b[8]; ld8(r, C_CC, a); ld8(r, C_CX, b);
; #pragma unroll
;         for (int e = 0; e < 8; ++e) o[e] = a[e] * b[e]; };
; #pragma unroll
;     for (int e = 0; e < 8; ++e) { y2[e] = 0.f; y1[e] = 0.f; }
;     if (s0 >= 2) ycx(r0 - 2, y2);
;     if (s0 >= 1) ycx(r0 - 1, y1);
;     for (int i = 0; i < 16; ++i) {
;         const int r = r0 + i; float y0[8], bb[8], zz[8], o[8]; ycx(r, y0); ld8(r, C_CB, bb); ld8(r, C_CZ, zz);
.LBB0_153:
	s_andn2_saveexec_b64 s[0:1], s[0:1]
	v_mov_b32_e32 v0, v1
	v_mov_b64_e32 v[40:41], v[0:1]
	v_mov_b64_e32 v[38:39], v[0:1]
	v_mov_b64_e32 v[36:37], v[0:1]
	v_mov_b64_e32 v[34:35], v[0:1]
	v_mov_b64_e32 v[46:47], v[0:1]
	v_mov_b64_e32 v[48:49], v[0:1]
	v_mov_b64_e32 v[58:59], v[0:1]
	v_mov_b64_e32 v[60:61], v[0:1]
	s_or_b64 exec, exec, s[0:1]
	s_add_i32 s0, s20, 0xfffbc000
	v_add_u32_e32 v28, s0, v28
	v_ashrrev_i32_e32 v29, 31, v28
	v_lshlrev_b64 v[28:29], 10, v[28:29]
	v_lshl_add_u64 v[42:43], s[16:17], 0, v[28:29]
	v_mov_b64_e32 v[28:29], s[14:15]
	s_waitcnt vmcnt(0)
	v_mov_b32_e32 v0, v7
	v_mov_b32_e32 v7, v9
	v_mov_b32_e32 v9, v3
	v_mov_b32_e32 v3, v5
	v_mad_i64_i32 v[44:45], s[0:1], v27, s33, v[28:29]
	s_waitcnt vmcnt(1)
	v_swap_b32 v5, v20
	v_mov_b32_e32 v3, v18
	v_mov_b32_e32 v18, v9
	s_waitcnt vmcnt(0)
	v_mov_b32_e32 v9, v24
	v_mov_b32_e32 v24, v7
	v_mov_b32_e32 v7, v22
	v_mov_b32_e32 v22, v0
	v_lshlrev_b32_e32 v0, 1, v26
	s_mov_b32 s0, 16
	v_lshl_add_u64 v[98:99], v[44:45], 0, v[0:1]
	v_add_co_u32_e32 v100, vcc, 0x1000, v98
	s_nop 1
	v_addc_co_u32_e32 v101, vcc, 0, v99, vcc
	v_add_co_u32_e32 v102, vcc, s84, v98
	s_nop 1
	v_addc_co_u32_e32 v103, vcc, 0, v99, vcc
	global_load_dwordx4 v[66:69], v[100:101], off offset:3072
	global_load_dwordx4 v[70:73], v[102:103], off
	global_load_dwordx4 v[74:77], v[100:101], off offset:2048
	global_load_dwordx4 v[78:81], v[102:103], off offset:1024
	s_mov_b64 s[22:23], 0x5800
	v_lshl_add_u64 v[100:101], v[100:101], 0, s[22:23]
	v_lshl_add_u64 v[102:103], v[102:103], 0, s[22:23]
	global_load_dwordx4 v[82:85], v[100:101], off offset:3072
	global_load_dwordx4 v[86:89], v[102:103], off
	global_load_dwordx4 v[90:93], v[100:101], off offset:2048
	global_load_dwordx4 v[94:97], v[102:103], off offset:1024
	s_mov_b64 s[22:23], 0x5800
	v_lshl_add_u64 v[100:101], v[100:101], 0, s[22:23]
	v_lshl_add_u64 v[102:103], v[102:103], 0, s[22:23]
	global_load_dwordx4 v[104:107], v[100:101], off offset:3072
	global_load_dwordx4 v[108:111], v[102:103], off
	global_load_dwordx4 v[112:115], v[100:101], off offset:2048
	global_load_dwordx4 v[116:119], v[102:103], off offset:1024
.Lconv4_0:
	s_cmp_lt_u32 s0, 4
	s_cbranch_scc1 .Lconv4_np_0
	s_mov_b64 s[22:23], 0x5800
	v_lshl_add_u64 v[100:101], v[100:101], 0, s[22:23]
	v_lshl_add_u64 v[102:103], v[102:103], 0, s[22:23]
	global_load_dwordx4 v[120:123], v[100:101], off offset:3072
	global_load_dwordx4 v[124:127], v[102:103], off
	global_load_dwordx4 v[128:131], v[100:101], off offset:2048
	global_load_dwordx4 v[132:135], v[102:103], off offset:1024
	s_waitcnt vmcnt(15)
	s_cmp_lt_u32 s0, 14
	s_cbranch_scc1 .Lconv4_go_0
	s_waitcnt vmcnt(12)
	s_branch .Lconv4_go_0

; __device__ __forceinline__ unsigned cvtpk(float lo, float hi) { unsigned r; asm volatile("v_cvt_pk_bf16_f32 %0, %1, %2" : "=v"(r) : "v"(lo), "v"(hi)); return r; }
; __device__ __forceinline__ float siluf_(float x) { return x * sigmoidf_(x); }
; __device__ __forceinline__ void item_conv(const Params& p, int l, int it) {
;     ...
;     for (int i = 0; i < 16; ++i) {
;         const int r = r0 + i; float y0[8], bb[8], zz[8], o[8]; ycx(r, y0); ld8(r, C_CB, bb); ld8(r, C_CZ, zz);
; #pragma unroll
;         for (int e = 0; e < 8; ++e) { o[e] = bb[e] * (w0[e] * y2[e] + w1[e] * y1[e] + w2[e] * y0[e]) * siluf_(zz[e]); y2[e] = y1[e]; y1[e] = y0[e]; }
;         u32x4 ow = {cvtpk(o[0], o[1]), cvtpk(o[2], o[3]), cvtpk(o[4], o[5]), cvtpk(o[6], o[7])};
;         *(u32x4*)(p.ybuf + ((size_t)2 * MG + r) * 512 + cc * 8) = ow;
.Lconv4_1:
	s_cmp_lt_u32 s0, 4
	s_cbranch_scc1 .Lconv4_np_1
	s_mov_b64 s[22:23], 0x5800
	v_lshl_add_u64 v[100:101], v[100:101], 0, s[22:23]
	v_lshl_add_u64 v[102:103], v[102:103], 0, s[22:23]
	global_load_dwordx4 v[66:69], v[100:101], off offset:3072
	global_load_dwordx4 v[70:73], v[102:103], off
	global_load_dwordx4 v[74:77], v[100:101], off offset:2048
	global_load_dwordx4 v[78:81], v[102:103], off offset:1024
	s_waitcnt vmcnt(15)
	s_cmp_lt_u32 s0, 14
	s_cbranch_scc1 .Lconv4_go_1
	s_waitcnt vmcnt(13)
	s_branch .Lconv4_go_1
.Lconv4_np_1:
	s_waitcnt vmcnt(11)
.Lconv4_go_1:
	v_lshl_add_u64 v[30:31], v[44:45], 0, v[0:1]
	v_add_co_u32_e32 v62, vcc, 0x1000, v30
	v_mov_b64_e32 v[50:51], v[34:35]
	s_nop 0
	v_addc_co_u32_e32 v63, vcc, 0, v31, vcc
	v_add_co_u32_e32 v64, vcc, s84, v30
	v_mov_b32_e32 v26, v82
	v_mov_b32_e32 v27, v83
	v_mov_b32_e32 v28, v84
	v_mov_b32_e32 v29, v85
	s_nop 0
	v_addc_co_u32_e32 v65, vcc, 0, v31, vcc
	v_mov_b32_e32 v30, v86
	v_mov_b32_e32 v31, v87
	v_mov_b32_e32 v32, v88
	v_mov_b32_e32 v33, v89
	v_mov_b64_e32 v[52:53], v[36:37]
	v_mov_b64_e32 v[54:55], v[38:39]
	v_mov_b64_e32 v[56:57], v[40:41]
	s_mov_b64 s[22:23], 0x400
	s_add_i32 s0, s0, -1
	s_cmp_eq_u32 s0, 0
	v_and_b32_e32 v34, 0xffff0000, v26
	v_lshlrev_b32_e32 v35, 16, v26
	v_and_b32_e32 v26, 0xffff0000, v27
	v_and_b32_e32 v36, 0xffff0000, v30
	v_lshlrev_b32_e32 v37, 16, v30
	v_lshlrev_b32_e32 v27, 16, v27
	v_and_b32_e32 v30, 0xffff0000, v31
	v_lshlrev_b32_e32 v31, 16, v31
	v_pk_mul_f32 v[34:35], v[34:35], v[36:37]
	v_pk_mul_f32 v[36:37], v[26:27], v[30:31]
	v_and_b32_e32 v26, 0xffff0000, v28
	v_lshlrev_b32_e32 v27, 16, v28
	v_and_b32_e32 v30, 0xffff0000, v32
	v_lshlrev_b32_e32 v31, 16, v32
	v_pk_mul_f32 v[38:39], v[26:27], v[30:31]
	v_and_b32_e32 v26, 0xffff0000, v29
	v_lshlrev_b32_e32 v27, 16, v29
	v_and_b32_e32 v28, 0xffff0000, v33
	v_lshlrev_b32_e32 v29, 16, v33
	v_pk_mul_f32 v[40:41], v[26:27], v[28:29]
	v_mov_b32_e32 v26, v90
	v_mov_b32_e32 v27, v91
	v_mov_b32_e32 v28, v92
	v_mov_b32_e32 v29, v93
	v_mov_b32_e32 v30, v94
	v_mov_b32_e32 v31, v95
	v_mov_b32_e32 v32, v96
	v_mov_b32_e32 v33, v97
	v_mov_b32_e32 v62, v61
	v_mov_b32_e32 v63, v35
	v_pk_mul_f32 v[62:63], v[6:7], v[62:63]
	v_lshlrev_b32_e32 v64, 16, v26
	v_fma_f32 v61, v14, v51, v62
	v_lshlrev_b32_e32 v65, 16, v30
	v_add_f32_e32 v62, v61, v63
	v_mul_f32_e32 v61, 0xbfb8aa3b, v65
	v_exp_f32_e32 v61, v61
	s_nop 0
	v_add_f32_e32 v61, 1.0, v61
	v_rcp_f32_e32 v63, v61
	v_mov_b32_e32 v61, v34
	v_pk_mul_f32 v[60:61], v[22:23], v[60:61]
	v_pk_mul_f32 v[62:63], v[62:63], v[64:65]
	s_nop 0
	v_mul_f32_e32 v64, v62, v63
	v_and_b32_e32 v63, 0xffff0000, v30
	v_and_b32_e32 v62, 0xffff0000, v26
	v_mul_f32_e32 v26, 0xbfb8aa3b, v63
	v_exp_f32_e32 v26, v26
	v_fma_f32 v60, v15, v50, v60
	v_add_f32_e32 v60, v60, v61
	v_and_b32_e32 v30, 0xffff0000, v27
	v_add_f32_e32 v26, 1.0, v26
	v_rcp_f32_e32 v61, v26
	s_nop 0
	v_pk_mul_f32 v[60:61], v[60:61], v[62:63]
	s_nop 0
	v_mul_f32_e32 v65, v60, v61
	v_mov_b32_e32 v60, v59
	v_mov_b32_e32 v61, v37
	v_lshlrev_b32_e32 v63, 16, v31
	v_and_b32_e32 v31, 0xffff0000, v31
	v_pk_mul_f32 v[60:61], v[8:9], v[60:61]
	v_lshlrev_b32_e32 v62, 16, v27
	v_mul_f32_e32 v27, 0xbfb8aa3b, v31
	v_fma_f32 v26, v16, v53, v60
	v_exp_f32_e32 v27, v27
	v_add_f32_e32 v60, v26, v61
	v_mul_f32_e32 v26, 0xbfb8aa3b, v63
	v_exp_f32_e32 v26, v26
	v_add_f32_e32 v27, 1.0, v27
	v_mov_b32_e32 v59, v36
	v_rcp_f32_e32 v27, v27
	v_add_f32_e32 v26, 1.0, v26
	v_pk_mul_f32 v[58:59], v[24:25], v[58:59]
	v_rcp_f32_e32 v61, v26
	v_fma_f32 v26, v17, v52, v58
	v_add_f32_e32 v26, v26, v59
	v_pk_mul_f32 v[26:27], v[26:27], v[30:31]
	v_lshlrev_b32_e32 v31, 16, v32
	v_mul_f32_e32 v58, v26, v27
	v_mov_b32_e32 v26, v49
	v_mov_b32_e32 v27, v39
	v_pk_mul_f32 v[26:27], v[2:3], v[26:27]
	v_lshlrev_b32_e32 v30, 16, v28
	v_fma_f32 v26, v10, v55, v26
	v_add_f32_e32 v26, v26, v27
	v_mul_f32_e32 v27, 0xbfb8aa3b, v31
	v_exp_f32_e32 v27, v27
	v_mov_b32_e32 v49, v38
	v_pk_mul_f32 v[60:61], v[60:61], v[62:63]
	v_add_f32_e32 v27, 1.0, v27
	v_rcp_f32_e32 v27, v27
	v_mul_f32_e32 v60, v60, v61
	v_pk_mul_f32 v[26:27], v[26:27], v[30:31]
	s_nop 0
	v_mul_f32_e32 v59, v26, v27
	v_pk_mul_f32 v[26:27], v[18:19], v[48:49]
	v_and_b32_e32 v31, 0xffff0000, v32
	v_fma_f32 v26, v11, v54, v26
	v_add_f32_e32 v26, v26, v27
	v_mul_f32_e32 v27, 0xbfb8aa3b, v31
	v_exp_f32_e32 v27, v27
	v_and_b32_e32 v30, 0xffff0000, v28
	v_mov_b64_e32 v[48:49], v[54:55]
	v_add_f32_e32 v27, 1.0, v27
	v_rcp_f32_e32 v27, v27
	s_nop 0
	v_pk_mul_f32 v[26:27], v[26:27], v[30:31]
	s_nop 0
	v_mul_f32_e32 v28, v26, v27
	v_mov_b32_e32 v26, v47
	v_mov_b32_e32 v27, v41
	v_pk_mul_f32 v[26:27], v[4:5], v[26:27]
	v_lshlrev_b32_e32 v31, 16, v33
	v_fma_f32 v26, v12, v57, v26
	v_add_f32_e32 v26, v26, v27
	v_mul_f32_e32 v27, 0xbfb8aa3b, v31
	v_exp_f32_e32 v27, v27
	v_lshlrev_b32_e32 v30, 16, v29
	v_mov_b32_e32 v47, v40
	v_add_f32_e32 v27, 1.0, v27
	v_rcp_f32_e32 v27, v27
	s_nop 0
	v_pk_mul_f32 v[26:27], v[26:27], v[30:31]
	s_nop 0
	v_mul_f32_e32 v32, v26, v27
	v_pk_mul_f32 v[26:27], v[20:21], v[46:47]
	v_and_b32_e32 v31, 0xffff0000, v33
	v_fma_f32 v26, v13, v56, v26
	v_add_f32_e32 v26, v26, v27
	v_mul_f32_e32 v27, 0xbfb8aa3b, v31
	v_exp_f32_e32 v27, v27
	v_and_b32_e32 v30, 0xffff0000, v29
	v_mov_b64_e32 v[46:47], v[56:57]
	v_add_f32_e32 v27, 1.0, v27
	v_rcp_f32_e32 v27, v27
	s_nop 0
	v_pk_mul_f32 v[26:27], v[26:27], v[30:31]
	v_lshl_add_u64 v[30:31], v[42:43], 0, v[0:1]
	v_lshl_add_u64 v[42:43], v[42:43], 0, s[22:23]
	s_mov_b64 s[22:23], 0x5800
	v_mul_f32_e32 v29, v26, v27
	v_cvt_pk_bf16_f32 v26, v64, v65
	v_cvt_pk_bf16_f32 v27, v60, v58
	v_cvt_pk_bf16_f32 v28, v59, v28
	v_lshl_add_u64 v[44:45], v[44:45], 0, s[22:23]
	v_mov_b64_e32 v[58:59], v[52:53]
	v_mov_b64_e32 v[60:61], v[50:51]
	v_cvt_pk_bf16_f32 v29, v32, v29
	global_store_dwordx4 v[30:31], v[26:29], off
	s_cbranch_scc0 .Lconv4_2
	s_branch .Lconv_done
.Lconv4_2:
	s_cmp_lt_u32 s0, 4
	s_cbranch_scc1 .Lconv4_np_2
	s_mov_b64 s[22:23], 0x5800
	v_lshl_add_u64 v[100:101], v[100:101], 0, s[22:23]
	v_lshl_add_u64 v[102:103], v[102:103], 0, s[22:23]
	global_load_dwordx4 v[82:85], v[100:101], off offset:3072
	global_load_dwordx4 v[86:89], v[102:103], off
	global_load_dwordx4 v[90:93], v[100:101], off offset:2048
	global_load_dwordx4 v[94:97], v[102:103], off offset:1024
	s_waitcnt vmcnt(15)
	s_cmp_lt_u32 s0, 14
	s_cbranch_scc1 .Lconv4_go_2
	s_waitcnt vmcnt(14)
	s_branch .Lconv4_go_2

; __device__ __forceinline__ unsigned cvtpk(float lo, float hi) { unsigned r; asm volatile("v_cvt_pk_bf16_f32 %0, %1, %2" : "=v"(r) : "v"(lo), "v"(hi)); return r; }
; __device__ __forceinline__ float siluf_(float x) { return x * sigmoidf_(x); }
; __device__ __forceinline__ void item_conv(const Params& p, int l, int it) {
;     ...
;     for (int i = 0; i < 16; ++i) {
;         const int r = r0 + i; float y0[8], bb[8], zz[8], o[8]; ycx(r, y0); ld8(r, C_CB, bb); ld8(r, C_CZ, zz);
; #pragma unroll
;         for (int e = 0; e < 8; ++e) { o[e] = bb[e] * (w0[e] * y2[e] + w1[e] * y1[e] + w2[e] * y0[e]) * siluf_(zz[e]); y2[e] = y1[e]; y1[e] = y0[e]; }
;         u32x4 ow = {cvtpk(o[0], o[1]), cvtpk(o[2], o[3]), cvtpk(o[4], o[5]), cvtpk(o[6], o[7])};
;         *(u32x4*)(p.ybuf + ((size_t)2 * MG + r) * 512 + cc * 8) = ow;
.Lconv4_go_2:
	v_lshl_add_u64 v[30:31], v[44:45], 0, v[0:1]
	v_add_co_u32_e32 v62, vcc, 0x1000, v30
	v_mov_b64_e32 v[50:51], v[34:35]
	s_nop 0
	v_addc_co_u32_e32 v63, vcc, 0, v31, vcc
	v_add_co_u32_e32 v64, vcc, s84, v30
	v_mov_b32_e32 v26, v104
	v_mov_b32_e32 v27, v105
	v_mov_b32_e32 v28, v106
	v_mov_b32_e32 v29, v107
	s_nop 0
	v_addc_co_u32_e32 v65, vcc, 0, v31, vcc
	v_mov_b32_e32 v30, v108
	v_mov_b32_e32 v31, v109
	v_mov_b32_e32 v32, v110
	v_mov_b32_e32 v33, v111
	v_mov_b64_e32 v[52:53], v[36:37]
	v_mov_b64_e32 v[54:55], v[38:39]
	v_mov_b64_e32 v[56:57], v[40:41]
	s_mov_b64 s[22:23], 0x400
	s_add_i32 s0, s0, -1
	s_cmp_eq_u32 s0, 0
	v_and_b32_e32 v34, 0xffff0000, v26
	v_lshlrev_b32_e32 v35, 16, v26
	v_and_b32_e32 v26, 0xffff0000, v27
	v_and_b32_e32 v36, 0xffff0000, v30
	v_lshlrev_b32_e32 v37, 16, v30
	v_lshlrev_b32_e32 v27, 16, v27
	v_and_b32_e32 v30, 0xffff0000, v31
	v_lshlrev_b32_e32 v31, 16, v31
	v_pk_mul_f32 v[34:35], v[34:35], v[36:37]
	v_pk_mul_f32 v[36:37], v[26:27], v[30:31]
	v_and_b32_e32 v26, 0xffff0000, v28
	v_lshlrev_b32_e32 v27, 16, v28
	v_and_b32_e32 v30, 0xffff0000, v32
	v_lshlrev_b32_e32 v31, 16, v32
	v_pk_mul_f32 v[38:39], v[26:27], v[30:31]
	v_and_b32_e32 v26, 0xffff0000, v29
	v_lshlrev_b32_e32 v27, 16, v29
	v_and_b32_e32 v28, 0xffff0000, v33
	v_lshlrev_b32_e32 v29, 16, v33
	v_pk_mul_f32 v[40:41], v[26:27], v[28:29]
	v_mov_b32_e32 v26, v112
	v_mov_b32_e32 v27, v113
	v_mov_b32_e32 v28, v114
	v_mov_b32_e32 v29, v115
	v_mov_b32_e32 v30, v116
	v_mov_b32_e32 v31, v117
	v_mov_b32_e32 v32, v118
	v_mov_b32_e32 v33, v119
	v_mov_b32_e32 v62, v61
	v_mov_b32_e32 v63, v35
	v_pk_mul_f32 v[62:63], v[6:7], v[62:63]
	v_lshlrev_b32_e32 v64, 16, v26
	v_fma_f32 v61, v14, v51, v62
	v_lshlrev_b32_e32 v65, 16, v30
	v_add_f32_e32 v62, v61, v63
	v_mul_f32_e32 v61, 0xbfb8aa3b, v65
	v_exp_f32_e32 v61, v61
	s_nop 0
	v_add_f32_e32 v61, 1.0, v61
	v_rcp_f32_e32 v63, v61
	v_mov_b32_e32 v61, v34
	v_pk_mul_f32 v[60:61], v[22:23], v[60:61]
	v_pk_mul_f32 v[62:63], v[62:63], v[64:65]
	s_nop 0
	v_mul_f32_e32 v64, v62, v63
	v_and_b32_e32 v63, 0xffff0000, v30
	v_and_b32_e32 v62, 0xffff0000, v26
	v_mul_f32_e32 v26, 0xbfb8aa3b, v63
	v_exp_f32_e32 v26, v26
	v_fma_f32 v60, v15, v50, v60
	v_add_f32_e32 v60, v60, v61
	v_and_b32_e32 v30, 0xffff0000, v27
	v_add_f32_e32 v26, 1.0, v26
	v_rcp_f32_e32 v61, v26
	s_nop 0
	v_pk_mul_f32 v[60:61], v[60:61], v[62:63]
	s_nop 0
	v_mul_f32_e32 v65, v60, v61
	v_mov_b32_e32 v60, v59
	v_mov_b32_e32 v61, v37
	v_lshlrev_b32_e32 v63, 16, v31
	v_and_b32_e32 v31, 0xffff0000, v31
	v_pk_mul_f32 v[60:61], v[8:9], v[60:61]
	v_lshlrev_b32_e32 v62, 16, v27
	v_mul_f32_e32 v27, 0xbfb8aa3b, v31
	v_fma_f32 v26, v16, v53, v60
	v_exp_f32_e32 v27, v27
	v_add_f32_e32 v60, v26, v61
	v_mul_f32_e32 v26, 0xbfb8aa3b, v63
	v_exp_f32_e32 v26, v26
	v_add_f32_e32 v27, 1.0, v27
	v_mov_b32_e32 v59, v36
	v_rcp_f32_e32 v27, v27
	v_add_f32_e32 v26, 1.0, v26
	v_pk_mul_f32 v[58:59], v[24:25], v[58:59]
	v_rcp_f32_e32 v61, v26
	v_fma_f32 v26, v17, v52, v58
	v_add_f32_e32 v26, v26, v59
	v_pk_mul_f32 v[26:27], v[26:27], v[30:31]
	v_lshlrev_b32_e32 v31, 16, v32
	v_mul_f32_e32 v58, v26, v27
	v_mov_b32_e32 v26, v49
	v_mov_b32_e32 v27, v39
	v_pk_mul_f32 v[26:27], v[2:3], v[26:27]
	v_lshlrev_b32_e32 v30, 16, v28
	v_fma_f32 v26, v10, v55, v26
	v_add_f32_e32 v26, v26, v27
	v_mul_f32_e32 v27, 0xbfb8aa3b, v31
	v_exp_f32_e32 v27, v27
	v_mov_b32_e32 v49, v38
	v_pk_mul_f32 v[60:61], v[60:61], v[62:63]
	v_add_f32_e32 v27, 1.0, v27
	v_rcp_f32_e32 v27, v27
	v_mul_f32_e32 v60, v60, v61
	v_pk_mul_f32 v[26:27], v[26:27], v[30:31]
	s_nop 0
	v_mul_f32_e32 v59, v26, v27
	v_pk_mul_f32 v[26:27], v[18:19], v[48:49]
	v_and_b32_e32 v31, 0xffff0000, v32
	v_fma_f32 v26, v11, v54, v26
	v_add_f32_e32 v26, v26, v27
	v_mul_f32_e32 v27, 0xbfb8aa3b, v31
	v_exp_f32_e32 v27, v27
	v_and_b32_e32 v30, 0xffff0000, v28
	v_mov_b64_e32 v[48:49], v[54:55]
	v_add_f32_e32 v27, 1.0, v27
	v_rcp_f32_e32 v27, v27
	s_nop 0
	v_pk_mul_f32 v[26:27], v[26:27], v[30:31]
	s_nop 0
	v_mul_f32_e32 v28, v26, v27
	v_mov_b32_e32 v26, v47
	v_mov_b32_e32 v27, v41
	v_pk_mul_f32 v[26:27], v[4:5], v[26:27]
	v_lshlrev_b32_e32 v31, 16, v33
	v_fma_f32 v26, v12, v57, v26
	v_add_f32_e32 v26, v26, v27
	v_mul_f32_e32 v27, 0xbfb8aa3b, v31
	v_exp_f32_e32 v27, v27
	v_lshlrev_b32_e32 v30, 16, v29
	v_mov_b32_e32 v47, v40
	v_add_f32_e32 v27, 1.0, v27
	v_rcp_f32_e32 v27, v27
	s_nop 0
	v_pk_mul_f32 v[26:27], v[26:27], v[30:31]
	s_nop 0
	v_mul_f32_e32 v32, v26, v27
	v_pk_mul_f32 v[26:27], v[20:21], v[46:47]
	v_and_b32_e32 v31, 0xffff0000, v33
	v_fma_f32 v26, v13, v56, v26
	v_add_f32_e32 v26, v26, v27
	v_mul_f32_e32 v27, 0xbfb8aa3b, v31
	v_exp_f32_e32 v27, v27
	v_and_b32_e32 v30, 0xffff0000, v29
	v_mov_b64_e32 v[46:47], v[56:57]
	v_add_f32_e32 v27, 1.0, v27
	v_rcp_f32_e32 v27, v27
	s_nop 0
	v_pk_mul_f32 v[26:27], v[26:27], v[30:31]
	v_lshl_add_u64 v[30:31], v[42:43], 0, v[0:1]
	v_lshl_add_u64 v[42:43], v[42:43], 0, s[22:23]
	s_mov_b64 s[22:23], 0x5800
	v_mul_f32_e32 v29, v26, v27
	v_cvt_pk_bf16_f32 v26, v64, v65
	v_cvt_pk_bf16_f32 v27, v60, v58
	v_cvt_pk_bf16_f32 v28, v59, v28
	v_lshl_add_u64 v[44:45], v[44:45], 0, s[22:23]
	v_mov_b64_e32 v[58:59], v[52:53]
	v_mov_b64_e32 v[60:61], v[50:51]
	v_cvt_pk_bf16_f32 v29, v32, v29
	global_store_dwordx4 v[30:31], v[26:29], off
	s_cbranch_scc0 .Lconv4_3
	s_branch .Lconv_done
.Lconv4_3:
	s_cmp_lt_u32 s0, 4
	s_cbranch_scc1 .Lconv4_np_3
	s_mov_b64 s[22:23], 0x5800
	v_lshl_add_u64 v[100:101], v[100:101], 0, s[22:23]
	v_lshl_add_u64 v[102:103], v[102:103], 0, s[22:23]
	global_load_dwordx4 v[104:107], v[100:101], off offset:3072
	global_load_dwordx4 v[108:111], v[102:103], off
	global_load_dwordx4 v[112:115], v[100:101], off offset:2048
	global_load_dwordx4 v[116:119], v[102:103], off offset:1024
	s_waitcnt vmcnt(15)
	s_branch .Lconv4_go_3
; __device__ __forceinline__ unsigned cvtpk(float lo, float hi) { unsigned r; asm volatile("v_cvt_pk_bf16_f32 %0, %1, %2" : "=v"(r) : "v"(lo), "v"(hi)); return r; }
; __device__ __forceinline__ float siluf_(float x) { return x * sigmoidf_(x); }
; __device__ __forceinline__ void item_conv(const Params& p, int l, int it) {
;     ...
;     for (int i = 0; i < 16; ++i) {
;         const int r = r0 + i; float y0[8], bb[8], zz[8], o[8]; ycx(r, y0); ld8(r, C_CB, bb); ld8(r, C_CZ, zz);
; #pragma unroll
;         for (int e = 0; e < 8; ++e) { o[e] = bb[e] * (w0[e] * y2[e] + w1[e] * y1[e] + w2[e] * y0[e]) * siluf_(zz[e]); y2[e] = y1[e]; y1[e] = y0[e]; }
;         u32x4 ow = {cvtpk(o[0], o[1]), cvtpk(o[2], o[3]), cvtpk(o[4], o[5]), cvtpk(o[6], o[7])};
;         *(u32x4*)(p.ybuf + ((size_t)2 * MG + r) * 512 + cc * 8) = ow;
.Lconv4_np_3:
	s_waitcnt vmcnt(3)
.Lconv4_go_3:
	v_lshl_add_u64 v[30:31], v[44:45], 0, v[0:1]
	v_add_co_u32_e32 v62, vcc, 0x1000, v30
	v_mov_b64_e32 v[50:51], v[34:35]
	s_nop 0
	v_addc_co_u32_e32 v63, vcc, 0, v31, vcc
	v_add_co_u32_e32 v64, vcc, s84, v30
	v_mov_b32_e32 v26, v120
	v_mov_b32_e32 v27, v121
	v_mov_b32_e32 v28, v122
	v_mov_b32_e32 v29, v123
	s_nop 0
	v_addc_co_u32_e32 v65, vcc, 0, v31, vcc
	v_mov_b32_e32 v30, v124
	v_mov_b32_e32 v31, v125
	v_mov_b32_e32 v32, v126
	v_mov_b32_e32 v33, v127
	v_mov_b64_e32 v[52:53], v[36:37]
	v_mov_b64_e32 v[54:55], v[38:39]
	v_mov_b64_e32 v[56:57], v[40:41]
	s_mov_b64 s[22:23], 0x400
	s_add_i32 s0, s0, -1
	s_cmp_eq_u32 s0, 0
	v_and_b32_e32 v34, 0xffff0000, v26
	v_lshlrev_b32_e32 v35, 16, v26
	v_and_b32_e32 v26, 0xffff0000, v27
	v_and_b32_e32 v36, 0xffff0000, v30
	v_lshlrev_b32_e32 v37, 16, v30
	v_lshlrev_b32_e32 v27, 16, v27
	v_and_b32_e32 v30, 0xffff0000, v31
	v_lshlrev_b32_e32 v31, 16, v31
	v_pk_mul_f32 v[34:35], v[34:35], v[36:37]
	v_pk_mul_f32 v[36:37], v[26:27], v[30:31]
	v_and_b32_e32 v26, 0xffff0000, v28
	v_lshlrev_b32_e32 v27, 16, v28
	v_and_b32_e32 v30, 0xffff0000, v32
	v_lshlrev_b32_e32 v31, 16, v32
	v_pk_mul_f32 v[38:39], v[26:27], v[30:31]
	v_and_b32_e32 v26, 0xffff0000, v29
	v_lshlrev_b32_e32 v27, 16, v29
	v_and_b32_e32 v28, 0xffff0000, v33
	v_lshlrev_b32_e32 v29, 16, v33
	v_pk_mul_f32 v[40:41], v[26:27], v[28:29]
	v_mov_b32_e32 v26, v128
	v_mov_b32_e32 v27, v129
	v_mov_b32_e32 v28, v130
	v_mov_b32_e32 v29, v131
	v_mov_b32_e32 v30, v132
	v_mov_b32_e32 v31, v133
	v_mov_b32_e32 v32, v134
	v_mov_b32_e32 v33, v135
	v_mov_b32_e32 v62, v61
	v_mov_b32_e32 v63, v35
	v_pk_mul_f32 v[62:63], v[6:7], v[62:63]
	v_lshlrev_b32_e32 v64, 16, v26
	v_fma_f32 v61, v14, v51, v62
	v_lshlrev_b32_e32 v65, 16, v30
	v_add_f32_e32 v62, v61, v63
	v_mul_f32_e32 v61, 0xbfb8aa3b, v65
	v_exp_f32_e32 v61, v61
	s_nop 0
	v_add_f32_e32 v61, 1.0, v61
	v_rcp_f32_e32 v63, v61
	v_mov_b32_e32 v61, v34
	v_pk_mul_f32 v[60:61], v[22:23], v[60:61]
	v_pk_mul_f32 v[62:63], v[62:63], v[64:65]
	s_nop 0
	v_mul_f32_e32 v64, v62, v63
	v_and_b32_e32 v63, 0xffff0000, v30
	v_and_b32_e32 v62, 0xffff0000, v26
	v_mul_f32_e32 v26, 0xbfb8aa3b, v63
	v_exp_f32_e32 v26, v26
	v_fma_f32 v60, v15, v50, v60
	v_add_f32_e32 v60, v60, v61
	v_and_b32_e32 v30, 0xffff0000, v27
	v_add_f32_e32 v26, 1.0, v26
	v_rcp_f32_e32 v61, v26
	s_nop 0
	v_pk_mul_f32 v[60:61], v[60:61], v[62:63]
	s_nop 0
	v_mul_f32_e32 v65, v60, v61
	v_mov_b32_e32 v60, v59
	v_mov_b32_e32 v61, v37
	v_lshlrev_b32_e32 v63, 16, v31
	v_and_b32_e32 v31, 0xffff0000, v31
	v_pk_mul_f32 v[60:61], v[8:9], v[60:61]
	v_lshlrev_b32_e32 v62, 16, v27
	v_mul_f32_e32 v27, 0xbfb8aa3b, v31
	v_fma_f32 v26, v16, v53, v60
	v_exp_f32_e32 v27, v27
	v_add_f32_e32 v60, v26, v61
	v_mul_f32_e32 v26, 0xbfb8aa3b, v63
	v_exp_f32_e32 v26, v26
	v_add_f32_e32 v27, 1.0, v27
	v_mov_b32_e32 v59, v36
	v_rcp_f32_e32 v27, v27
	v_add_f32_e32 v26, 1.0, v26
	v_pk_mul_f32 v[58:59], v[24:25], v[58:59]
	v_rcp_f32_e32 v61, v26
	v_fma_f32 v26, v17, v52, v58
	v_add_f32_e32 v26, v26, v59
	v_pk_mul_f32 v[26:27], v[26:27], v[30:31]
	v_lshlrev_b32_e32 v31, 16, v32
	v_mul_f32_e32 v58, v26, v27
	v_mov_b32_e32 v26, v49
	v_mov_b32_e32 v27, v39
	v_pk_mul_f32 v[26:27], v[2:3], v[26:27]
	v_lshlrev_b32_e32 v30, 16, v28
	v_fma_f32 v26, v10, v55, v26
	v_add_f32_e32 v26, v26, v27
	v_mul_f32_e32 v27, 0xbfb8aa3b, v31
	v_exp_f32_e32 v27, v27
	v_mov_b32_e32 v49, v38
	v_pk_mul_f32 v[60:61], v[60:61], v[62:63]
	v_add_f32_e32 v27, 1.0, v27
	v_rcp_f32_e32 v27, v27
	v_mul_f32_e32 v60, v60, v61
	v_pk_mul_f32 v[26:27], v[26:27], v[30:31]
	s_nop 0
	v_mul_f32_e32 v59, v26, v27
	v_pk_mul_f32 v[26:27], v[18:19], v[48:49]
	v_and_b32_e32 v31, 0xffff0000, v32
	v_fma_f32 v26, v11, v54, v26
	v_add_f32_e32 v26, v26, v27
	v_mul_f32_e32 v27, 0xbfb8aa3b, v31
	v_exp_f32_e32 v27, v27
	v_and_b32_e32 v30, 0xffff0000, v28
	v_mov_b64_e32 v[48:49], v[54:55]
	v_add_f32_e32 v27, 1.0, v27
	v_rcp_f32_e32 v27, v27
	s_nop 0
	v_pk_mul_f32 v[26:27], v[26:27], v[30:31]
	s_nop 0
	v_mul_f32_e32 v28, v26, v27
	v_mov_b32_e32 v26, v47
	v_mov_b32_e32 v27, v41
	v_pk_mul_f32 v[26:27], v[4:5], v[26:27]
	v_lshlrev_b32_e32 v31, 16, v33
	v_fma_f32 v26, v12, v57, v26
	v_add_f32_e32 v26, v26, v27
	v_mul_f32_e32 v27, 0xbfb8aa3b, v31
	v_exp_f32_e32 v27, v27
	v_lshlrev_b32_e32 v30, 16, v29
	v_mov_b32_e32 v47, v40
	v_add_f32_e32 v27, 1.0, v27
	v_rcp_f32_e32 v27, v27
	s_nop 0
	v_pk_mul_f32 v[26:27], v[26:27], v[30:31]
	s_nop 0
	v_mul_f32_e32 v32, v26, v27
	v_pk_mul_f32 v[26:27], v[20:21], v[46:47]
	v_and_b32_e32 v31, 0xffff0000, v33
	v_fma_f32 v26, v13, v56, v26
	v_add_f32_e32 v26, v26, v27
	v_mul_f32_e32 v27, 0xbfb8aa3b, v31
	v_exp_f32_e32 v27, v27
	v_and_b32_e32 v30, 0xffff0000, v29
	v_mov_b64_e32 v[46:47], v[56:57]
	v_add_f32_e32 v27, 1.0, v27
	v_rcp_f32_e32 v27, v27
	s_nop 0
	v_pk_mul_f32 v[26:27], v[26:27], v[30:31]
	v_lshl_add_u64 v[30:31], v[42:43], 0, v[0:1]
	v_lshl_add_u64 v[42:43], v[42:43], 0, s[22:23]
	s_mov_b64 s[22:23], 0x5800
	v_mul_f32_e32 v29, v26, v27
	v_cvt_pk_bf16_f32 v26, v64, v65
	v_cvt_pk_bf16_f32 v27, v60, v58
	v_cvt_pk_bf16_f32 v28, v59, v28
	v_lshl_add_u64 v[44:45], v[44:45], 0, s[22:23]
	v_mov_b64_e32 v[58:59], v[52:53]
	v_mov_b64_e32 v[60:61], v[50:51]
	v_cvt_pk_bf16_f32 v29, v32, v29
	global_store_dwordx4 v[30:31], v[26:29], off
	s_cbranch_scc0 .Lconv4_0

;     ...
;           int outp = 0, tie = 0;
; #pragma unroll
;           for (int r = 0; r < 64; ++r) {
;               if (r * 64 < n) {
;                   const bool gt = u[r] > T, eq = (u[r] == T);
;                   const unsigned long long meq = __ballot(eq);
;                   const int rank = tie + __builtin_amdgcn_mbcnt_hi((unsigned)(meq >> 32), __builtin_amdgcn_mbcnt_lo((unsigned)meq, 0));
;                   const bool s = gt || (eq && rank < need);
;                   const unsigned long long ms = __ballot(s);
;                   const int slot = outp + __builtin_amdgcn_mbcnt_hi((unsigned)(ms >> 32), __builtin_amdgcn_mbcnt_lo((unsigned)ms, 0));
;                   if (s) list[slot] = (u16)(r * 64 + lane);
;                   outp += __builtin_popcountll(ms); tie += __builtin_popcountll(meq);
.LBB0_803:
	s_andn2_b64 vcc, exec, s[84:85]
	s_cbranch_vccz .LBB0_884
	s_branch .LBB0_889
.Lfar_to_7:
	s_branch .LBB0_7
.LBB0_804:
	v_cmp_le_u32_e64 s[0:1], v51, v69
	v_cmp_eq_u32_e32 vcc, v51, v69
	s_mov_b64 s[20:21], -1
	s_and_saveexec_b64 s[22:23], s[0:1]
	v_mbcnt_lo_u32_b32 v70, vcc_lo, 0
	v_mbcnt_hi_u32_b32 v70, vcc_hi, v70
	v_add_u32_e32 v70, s26, v70
	v_cmp_gt_i32_e64 s[0:1], s24, v70
	s_and_b64 s[0:1], vcc, s[0:1]
	s_orn2_b64 s[20:21], s[0:1], exec
	s_or_b64 exec, exec, s[22:23]
	v_cndmask_b32_e64 v70, 0, 1, s[20:21]
	v_cmp_ne_u32_e64 s[0:1], 0, v70
	s_and_saveexec_b64 s[22:23], s[20:21]
	s_cbranch_execz .LBB0_808
	s_lshl_b32 s20, s25, 1
	v_mbcnt_lo_u32_b32 v71, s0, 0
	s_add_i32 s20, s56, s20
	v_mbcnt_hi_u32_b32 v71, s1, v71
	v_or_b32_e32 v70, 0xbc0, v163
	v_lshl_add_u32 v71, v71, 1, s20
	ds_write_b16 v71, v70
